# MIX lists: the 40 sample-chain partner blocks that run an RG-LRU scan hand their std-prompt item to neighbouring partner blocks (max partner list 61 -> 58 us est.)
# speedup vs baseline: 1.0019x; 1.0019x over previous
.Lms_y2:
	s_movk_i32 s2, 680
	s_cmpk_eq_u32 s1, 128
	s_cbranch_scc1 .Lms_set
	s_cmpk_eq_u32 s1, 680
	s_cbranch_scc0 .Lms_y2b
	s_movk_i32 s2, 256
	s_cmpk_lt_u32 s0, 0x1a8
	s_cbranch_scc1 .Lms_set
	s_movk_i32 s2, 936
	s_branch .Lms_set
.Lms_y2b:
	s_cmpk_eq_u32 s1, 936
	s_cbranch_scc0 .LBB0_1139
	s_movk_i32 s2, 896
	s_cmpk_lt_u32 s0, 0x1d0
	s_cbranch_scc0 .LBB0_1139
